# v35: conv_run loop-top wait leaves the previous tile's 4 stores outstanding (vmcnt(4)), prologue drains separately
# speedup vs baseline: 1.0116x; 1.0042x over previous
.LBB0_164:
	s_waitcnt vmcnt(4)
	v_mov_b64_e32 v[72:73], v[2:3]
	v_mov_b64_e32 v[74:75], v[4:5]
	v_mov_b64_e32 v[76:77], v[6:7]
	v_mov_b64_e32 v[78:79], v[8:9]
	v_mov_b64_e32 v[80:81], v[10:11]
	v_mov_b64_e32 v[82:83], v[12:13]
	v_mov_b64_e32 v[84:85], v[14:15]
	v_mov_b64_e32 v[86:87], v[16:17]
	v_mov_b64_e32 v[88:89], v[18:19]
	v_mov_b64_e32 v[90:91], v[20:21]
	v_mov_b64_e32 v[92:93], v[22:23]
	v_mov_b64_e32 v[94:95], v[24:25]
	v_mov_b64_e32 v[96:97], v[26:27]
	v_mov_b64_e32 v[98:99], v[28:29]
	v_mov_b64_e32 v[100:101], v[30:31]
	v_mov_b64_e32 v[102:103], v[32:33]
	v_mov_b64_e32 v[104:105], v[64:65]
	v_mov_b64_e32 v[106:107], v[66:67]
	v_mov_b64_e32 v[108:109], v[68:69]
	v_mov_b64_e32 v[110:111], v[70:71]
	s_add_i32 s10, s33, s38
	s_cmp_ge_i32 s10, s34
	s_cbranch_scc1 .LBB0_189
	s_cmpk_gt_i32 s10, 0xfe
	s_mov_b64 s[30:31], -1
	s_cbranch_scc0 .LBB0_178
	s_cmpk_gt_u32 s10, 0x4fe
	s_mov_b64 s[28:29], -1
	s_cbranch_scc0 .LBB0_176
	s_cmpk_gt_u32 s10, 0x8fe
	s_cbranch_scc0 .LBB0_173
	s_and_b32 s3, s35, 0x780
	s_cmpk_gt_u32 s10, 0x91e
	v_or_b32_e32 v4, s3, v1
	s_mov_b64 s[26:27], -1
	s_cbranch_scc0 .LBB0_170
	s_and_b32 s10, s36, 0xffffff80
	v_lshlrev_b32_e32 v2, 12, v4
	v_mov_b32_e32 v3, v37
	s_addk_i32 s10, 0xb700
	v_lshl_add_u64 v[2:3], s[12:13], 0, v[2:3]
	v_lshl_add_u64 v[2:3], s[10:11], 1, v[2:3]
	v_lshlrev_b32_e32 v6, 1, v38
	v_mov_b32_e32 v7, v37
	v_lshl_add_u64 v[42:43], v[2:3], 0, v[6:7]
	v_or_b32_e32 v2, s10, v46
	v_mov_b32_e32 v3, v37
	v_lshlrev_b64 v[2:3], 13, v[2:3]
	v_lshl_add_u64 v[2:3], s[76:77], 0, v[2:3]
	s_lshl_b32 s10, s3, 2
	v_lshl_add_u64 v[2:3], v[2:3], 0, s[10:11]
	s_mov_b64 s[26:27], 0

.LBB0_409:
	s_waitcnt vmcnt(4)
	v_mov_b64_e32 v[72:73], v[2:3]
	v_mov_b64_e32 v[74:75], v[4:5]
	v_mov_b64_e32 v[76:77], v[6:7]
	v_mov_b64_e32 v[78:79], v[8:9]
	v_mov_b64_e32 v[80:81], v[10:11]
	v_mov_b64_e32 v[82:83], v[12:13]
	v_mov_b64_e32 v[84:85], v[14:15]
	v_mov_b64_e32 v[86:87], v[16:17]
	v_mov_b64_e32 v[88:89], v[18:19]
	v_mov_b64_e32 v[90:91], v[20:21]
	v_mov_b64_e32 v[92:93], v[22:23]
	v_mov_b64_e32 v[94:95], v[24:25]
	v_mov_b64_e32 v[96:97], v[26:27]
	v_mov_b64_e32 v[98:99], v[28:29]
	v_mov_b64_e32 v[100:101], v[30:31]
	v_mov_b64_e32 v[102:103], v[32:33]
	s_add_i32 s35, s3, 1
	s_cmp_ge_i32 s35, s30
	s_cselect_b64 s[24:25], -1, 0
	s_and_b64 vcc, exec, s[24:25]
	s_mov_b32 s36, s2
	s_cbranch_vccnz .Lcvt_la
	s_cmpk_gt_i32 s3, 0xfe
	s_mov_b64 s[28:29], -1
	s_cbranch_scc0 .LBB0_423
	s_cmpk_gt_u32 s35, 0x4ff
	s_mov_b64 s[26:27], -1
	s_cbranch_scc0 .LBB0_421
	s_cmpk_gt_u32 s35, 0x8ff
	s_cbranch_scc0 .LBB0_418
	s_and_b32 s3, s33, 0x780
	s_cmpk_gt_u32 s35, 0x91f
	v_or_b32_e32 v4, s3, v1
	s_cbranch_scc0 .LBB0_415
	s_and_b32 s8, s31, 0xffffff80
	v_lshlrev_b32_e32 v2, 12, v4
	v_mov_b32_e32 v3, v39
	s_addk_i32 s8, 0xb700
	v_lshl_add_u64 v[2:3], s[10:11], 0, v[2:3]
	v_lshl_add_u64 v[2:3], s[8:9], 1, v[2:3]
	v_lshlrev_b32_e32 v6, 1, v36
	v_mov_b32_e32 v7, v39
	v_lshl_add_u64 v[42:43], v[2:3], 0, v[6:7]
	v_or_b32_e32 v2, s8, v37
	v_mov_b32_e32 v3, v39
	v_lshlrev_b64 v[2:3], 13, v[2:3]
	v_lshl_add_u64 v[2:3], s[76:77], 0, v[2:3]
	s_lshl_b32 s8, s3, 2
	v_lshl_add_u64 v[2:3], v[2:3], 0, s[8:9]
	s_mov_b64 s[26:27], 0

.LBB0_457:
	s_waitcnt vmcnt(4)
	v_mov_b64_e32 v[72:73], v[2:3]
	v_mov_b64_e32 v[74:75], v[4:5]
	v_mov_b64_e32 v[76:77], v[6:7]
	v_mov_b64_e32 v[78:79], v[8:9]
	v_mov_b64_e32 v[80:81], v[10:11]
	v_mov_b64_e32 v[82:83], v[12:13]
	v_mov_b64_e32 v[84:85], v[14:15]
	v_mov_b64_e32 v[86:87], v[16:17]
	v_mov_b64_e32 v[88:89], v[18:19]
	v_mov_b64_e32 v[90:91], v[20:21]
	v_mov_b64_e32 v[92:93], v[22:23]
	v_mov_b64_e32 v[94:95], v[24:25]
	v_mov_b64_e32 v[96:97], v[26:27]
	v_mov_b64_e32 v[98:99], v[28:29]
	v_mov_b64_e32 v[100:101], v[30:31]
	v_mov_b64_e32 v[102:103], v[32:33]
	v_mov_b64_e32 v[104:105], v[64:65]
	v_mov_b64_e32 v[106:107], v[66:67]
	v_mov_b64_e32 v[108:109], v[68:69]
	v_mov_b64_e32 v[110:111], v[70:71]
	s_add_i32 s6, s28, s34
	s_cmp_ge_i32 s6, s29
	s_cbranch_scc1 .LBB0_482
	s_cmpk_gt_i32 s6, 0xfe
	s_mov_b64 s[26:27], -1
	s_cbranch_scc0 .LBB0_471
	s_cmpk_gt_u32 s6, 0x4fe
	s_mov_b64 s[24:25], -1
	s_cbranch_scc0 .LBB0_469
	s_cmpk_gt_u32 s6, 0x8fe
	s_cbranch_scc0 .LBB0_466
	s_and_b32 s3, s30, 0x780
	s_cmpk_gt_u32 s6, 0x91e
	v_or_b32_e32 v4, s3, v1
	s_mov_b64 s[22:23], -1
	s_cbranch_scc0 .LBB0_463
	s_and_b32 s6, s31, 0xffffff80
	v_lshlrev_b32_e32 v2, 12, v4
	v_mov_b32_e32 v3, v37
	s_addk_i32 s6, 0xb700
	v_lshl_add_u64 v[2:3], s[8:9], 0, v[2:3]
	v_lshl_add_u64 v[2:3], s[6:7], 1, v[2:3]
	v_lshlrev_b32_e32 v6, 1, v38
	v_mov_b32_e32 v7, v37
	v_lshl_add_u64 v[42:43], v[2:3], 0, v[6:7]
	v_or_b32_e32 v2, s6, v48
	v_mov_b32_e32 v3, v37
	v_lshlrev_b64 v[2:3], 13, v[2:3]
	v_lshl_add_u64 v[2:3], s[76:77], 0, v[2:3]
	s_lshl_b32 s6, s3, 2
	v_lshl_add_u64 v[2:3], v[2:3], 0, s[6:7]
	s_mov_b64 s[22:23], 0
